# diff-attn: the older (kvg0) waves now also issue the partner group's next-tile LDS-DMA (mid-step), kvg1 waves issue none: balances the two SIMD partners
# speedup vs baseline: 1.0078x; 1.0008x over previous
; DI void diff_unit(unsigned char* smem, const bf16* __restrict__ QKV, bf16* __restrict__ Y, int h, int qb, float lam, float outscale, const float* __restrict__ gain, float kn0, float kn1, int tid) {
;     ...
;         const bool mine_next = (j - 2 >= 0);
;         if (mine_next) D3_DMA(j - 2, D3_BUF - bufo);
.LBB0_207:
	s_or_b64 exec, exec, s[12:13]
	s_and_b32 s45, s68, 0x10000
	v_cmp_gt_i32_e64 s[12:13], 4, v85
	v_cmp_lt_i32_e64 s[14:15], 3, v85
	v_readfirstlane_b32 s32, v85
	s_cmp_lg_u32 s61, 0
	s_cbranch_scc1 .Lmy_dma_top_skip
	s_and_saveexec_b64 s[16:17], s[14:15]
	s_cbranch_execz .LBB0_209
	v_add_u32_e32 v38, -4, v85
	v_mad_u64_u32 v[34:35], s[54:55], v38, s53, v[154:155]
	s_sub_i32 s47, s63, s45
	v_mad_u64_u32 v[38:39], s[54:55], v38, s53, v[156:157]
	v_lshl_add_u64 v[36:37], v[34:35], 0, s[86:87]
	s_add_i32 m0, s47, 0x10000
	s_add_i32 s54, s47, 0x14000
	global_load_lds_dwordx4 v[36:37], off
	s_mov_b32 m0, s54
	v_lshl_add_u64 v[36:37], v[34:35], 0, s[88:89]
	global_load_lds_dwordx4 v[38:39], off
	s_add_i32 m0, s47, 0x11000
	s_nop 0
	global_load_lds_dwordx4 v[36:37], off
	v_lshl_add_u64 v[36:37], v[38:39], 0, s[90:91]
	s_add_i32 m0, s47, 0x15000
	s_nop 0
	global_load_lds_dwordx4 v[36:37], off
	v_lshl_add_u64 v[36:37], v[34:35], 0, s[92:93]
	s_add_i32 m0, s47, 0x12000
	v_lshl_add_u64 v[34:35], v[34:35], 0, s[96:97]
	global_load_lds_dwordx4 v[36:37], off
	v_lshl_add_u64 v[36:37], v[38:39], 0, s[94:95]
	s_add_i32 m0, s47, 0x16000
	s_nop 0
	global_load_lds_dwordx4 v[36:37], off
	s_add_i32 m0, s47, 0x13000
	s_nop 0
	global_load_lds_dwordx4 v[34:35], off
	v_lshl_add_u64 v[34:35], v[38:39], 0, s[72:73]
	s_add_i32 m0, s47, 0x17000
	s_nop 0
	global_load_lds_dwordx4 v[34:35], off

; #define MFMA32(a, b, c) __builtin_amdgcn_mfma_f32_32x32x16_bf16((a), (b), (c), 0, 0, 0)
; DI void diff_unit(unsigned char* smem, const bf16* __restrict__ QKV, bf16* __restrict__ Y, int h, int qb, float lam, float outscale, const float* __restrict__ gain, float kn0, float kn1, int tid) {
;     ...
;         const bool mine_next = (j - 2 >= 0);
;         if (mine_next) D3_DMA(j - 2, D3_BUF - bufo);
;     ...
;                 for (int ds = 0; ds < 4; ++ds)
; #pragma unroll
;                     for (int kh = 0; kh < 2; ++kh) p[kh] = MFMA32(kf[kh * 4 + ds], qf[ds], p[kh]);
.Lmy_ci_join:
	s_waitcnt lgkmcnt(4)
	v_mfma_f32_32x32x16_bf16 v[80:95], v[136:139], v[116:119], v[80:95]
	v_mfma_f32_32x32x16_bf16 v[96:111], v[132:135], v[116:119], v[96:111]
	s_waitcnt lgkmcnt(2)
	v_mfma_f32_32x32x16_bf16 v[80:95], v[128:131], v[120:123], v[80:95]
	v_mfma_f32_32x32x16_bf16 v[96:111], v[42:45], v[120:123], v[96:111]
	s_waitcnt lgkmcnt(0)
	v_mfma_f32_32x32x16_bf16 v[80:95], v[38:41], v[124:127], v[80:95]
	v_mfma_f32_32x32x16_bf16 v[96:111], v[34:37], v[124:127], v[96:111]
	s_cmp_lg_u32 s61, 0
	s_cbranch_scc1 .Lmy_dma_mid_skip
	s_cmp_lt_i32 s32, 5
	s_cbranch_scc1 .Lmy_dma_mid_skip
	v_add_u32_e32 v214, -3, v192
	v_mul_lo_u32 v214, v214, s53
	v_mov_b32_e32 v215, 0
	s_sub_i32 s32, s63, s45
	s_add_i32 s32, s32, 0x8000
	v_lshl_add_u64 v[212:213], v[154:155], 0, v[214:215]
	v_lshl_add_u64 v[216:217], v[156:157], 0, v[214:215]
	v_lshl_add_u64 v[214:215], v[212:213], 0, s[86:87]
	s_add_i32 m0, s32, 0x10000
	s_nop 0
	global_load_lds_dwordx4 v[214:215], off
	s_add_i32 m0, s32, 0x14000
	v_lshl_add_u64 v[214:215], v[212:213], 0, s[88:89]
	global_load_lds_dwordx4 v[216:217], off
	s_add_i32 m0, s32, 0x11000
	s_nop 0
	global_load_lds_dwordx4 v[214:215], off
	v_lshl_add_u64 v[214:215], v[216:217], 0, s[90:91]
	s_add_i32 m0, s32, 0x15000
	s_nop 0
	global_load_lds_dwordx4 v[214:215], off
	v_lshl_add_u64 v[214:215], v[212:213], 0, s[92:93]
	s_add_i32 m0, s32, 0x12000
	v_lshl_add_u64 v[212:213], v[212:213], 0, s[96:97]
	global_load_lds_dwordx4 v[214:215], off
	v_lshl_add_u64 v[214:215], v[216:217], 0, s[94:95]
	s_add_i32 m0, s32, 0x16000
	s_nop 0
	global_load_lds_dwordx4 v[214:215], off
	s_add_i32 m0, s32, 0x13000
	s_nop 0
	global_load_lds_dwordx4 v[212:213], off
	v_lshl_add_u64 v[212:213], v[216:217], 0, s[72:73]
	s_add_i32 m0, s32, 0x17000
	s_nop 0
	global_load_lds_dwordx4 v[212:213], off

; DI void diff_unit(unsigned char* smem, const bf16* __restrict__ QKV, bf16* __restrict__ Y, int h, int qb, float lam, float outscale, const float* __restrict__ gain, float kn0, float kn1, int tid) {
;     ...
;         const bool mine_next = (j - 2 >= 0);
;         if (mine_next) D3_DMA(j - 2, D3_BUF - bufo);
.Lmy_dma_stub:
	s_cmp_lg_u32 s61, 0
	s_cbranch_scc1 .LBB0_222
	s_cmp_lt_i32 s32, 5
	s_cbranch_scc1 .LBB0_222
	s_mov_b64 exec, s[54:55]
	v_add_u32_e32 v214, -3, v192
	v_mul_lo_u32 v214, v214, s53
	v_mov_b32_e32 v215, 0
	s_sub_i32 s32, s63, s45
	s_add_i32 s32, s32, 0x8000
	v_lshl_add_u64 v[212:213], v[154:155], 0, v[214:215]
	v_lshl_add_u64 v[216:217], v[156:157], 0, v[214:215]
	v_lshl_add_u64 v[214:215], v[212:213], 0, s[86:87]
	s_add_i32 m0, s32, 0x10000
	s_nop 0
	global_load_lds_dwordx4 v[214:215], off
	s_add_i32 m0, s32, 0x14000
	v_lshl_add_u64 v[214:215], v[212:213], 0, s[88:89]
	global_load_lds_dwordx4 v[216:217], off
	s_add_i32 m0, s32, 0x11000
	s_nop 0
	global_load_lds_dwordx4 v[214:215], off
	v_lshl_add_u64 v[214:215], v[216:217], 0, s[90:91]
	s_add_i32 m0, s32, 0x15000
	s_nop 0
	global_load_lds_dwordx4 v[214:215], off
	v_lshl_add_u64 v[214:215], v[212:213], 0, s[92:93]
	s_add_i32 m0, s32, 0x12000
	v_lshl_add_u64 v[212:213], v[212:213], 0, s[96:97]
	global_load_lds_dwordx4 v[214:215], off
	v_lshl_add_u64 v[214:215], v[216:217], 0, s[94:95]
	s_add_i32 m0, s32, 0x16000
	s_nop 0
	global_load_lds_dwordx4 v[214:215], off
	s_add_i32 m0, s32, 0x13000
	s_nop 0
	global_load_lds_dwordx4 v[212:213], off
	v_lshl_add_u64 v[212:213], v[216:217], 0, s[72:73]
	s_add_i32 m0, s32, 0x17000
	s_nop 0
	global_load_lds_dwordx4 v[212:213], off
	s_branch .LBB0_222
